# WBR conversion moved from the phase-1 idle slot into phase 0 (fits the single conversion round there); phase-1 slot 2752 tiles
# speedup vs baseline: 1.0045x; 1.0045x over previous
; #define PH_BEGIN const int zi = opaque0(); unsigned char* ws = P.ws + zi; float* const OUT = P.out + zi; (void)OUT; const int tid = opqv((int)threadIdx.x); const int bid = opqs((int)blockIdx.x); const int G = opqs((int)gridDim.x); (void)tid; (void)bid; (void)G; unsigned char* WB = ws + WS_WB; float* SS = (float*)(ws + WS_SS); (void)WB; (void)SS; (void)zi;
; __global__ void __launch_bounds__(512) mega(Params P) {
;     ...
;             { PH_BEGIN convT_w<0>(INP(7) + (size_t)l * D * 6928, 6928, 3856, INP(5) + (size_t)l * D, (bf16_t*)(WB + WB_WG), D, D, 3072, bid * 8 + (tid >> 6), G * 8, tid & 63, 3136); }
;             for (int j = 0; j < 3; ++j) { PH_BEGIN convT_w<0>(INP(27) + ((size_t)l * 3 + j) * 512 * D, D, 0, nullptr, (bf16_t*)(WB + WB_WBR) + (size_t)j * D * 512, 512, 512, D, bid * 8 + (tid >> 6), G * 8, tid & 63, 3904 + 128 * j); }
.LBB0_708:
	s_or_b64 exec, exec, s[4:5]
	s_mov_b32 s101, 0
	s_cmp_eq_u32 s100, 2
	s_cbranch_scc1 .Lh708_done
	s_cmp_eq_u32 s3, 0x70
	s_cbranch_scc0 .Lh708_norm
	s_mov_b32 s101, 1
	s_or_b32 s2, s2, 0x10000
	s_mov_b32 s3, 0x100000
	s_branch .Lh708_done
.Lh708_norm:
	s_and_b32 s2, s2, 0xffff
	s_movk_i32 s3, 0x100

; #define PH_BEGIN const int zi = opaque0(); unsigned char* ws = P.ws + zi; float* const OUT = P.out + zi; (void)OUT; const int tid = opqv((int)threadIdx.x); const int bid = opqs((int)blockIdx.x); const int G = opqs((int)gridDim.x); (void)tid; (void)bid; (void)G; unsigned char* WB = ws + WS_WB; float* SS = (float*)(ws + WS_SS); (void)WB; (void)SS; (void)zi;
; __global__ void __launch_bounds__(512) mega(Params P) {
;     ...
;             for (int j = 0; j < 3; ++j) { PH_BEGIN convT_w<0>(INP(27) + ((size_t)l * 3 + j) * 512 * D, D, 0, nullptr, (bf16_t*)(WB + WB_WBR) + (size_t)j * D * 512, 512, 512, D, bid * 8 + (tid >> 6), G * 8, tid & 63, 3904 + 128 * j); }
;             { PH_BEGIN convT_w<0>(INP(28) + (size_t)l * D * D, D, 0, nullptr, (bf16_t*)(WB + WB_WO), D, D, D, bid * 8 + (tid >> 6), G * 8, tid & 63, 4288); }
.LBB0_715:
	s_cmp_eq_u32 s100, 2
	s_cbranch_scc1 .Lh715_done
	s_cmp_eq_u32 s101, 1
	s_cbranch_scc0 .Lh715_norm
	s_and_b32 s2, s2, 0xffff
	s_movk_i32 s3, 0x70
	s_branch .Lh715_done
.Lh715_norm:
	s_or_b32 s2, s2, 0x10000
	s_mov_b32 s3, 0x100000
